# attention prompt items run on the XCD that owns their query row block; sample-row attention output written through (sc1); XCD leader skips buffer_wbl2 after the attention phase too
# baseline (speedup 1.0000x reference)
.LBB0_155:
	s_and_b64 vcc, exec, s[8:9]
	s_cbranch_vccz .LBB0_221
	v_writelane_b32 v254, s38, 57
	v_mov_b32_e32 v0, v220
	s_load_dwordx4 s[8:11], s[0:1], 0xa8
	v_writelane_b32 v254, s39, 58
	s_nop 0
	v_readlane_b32 s6, v254, 45
	v_readlane_b32 s7, v254, 46
	s_mov_b32 s12, s6
	s_lshl_b32 s6, s6, 6
	s_ashr_i32 s7, s6, 31
	s_lshl_b32 s12, s12, 4
	s_ashr_i32 s13, s12, 31
	s_lshl_b64 s[6:7], s[6:7], 2
	s_waitcnt lgkmcnt(0)
	s_add_u32 s6, s8, s6
	s_addc_u32 s7, s9, s7
	v_writelane_b32 v255, s6, 9
	s_nop 1
	v_writelane_b32 v255, s7, 10
	s_lshl_b64 s[6:7], s[12:13], 2
	s_add_u32 s6, s10, s6
	s_addc_u32 s7, s11, s7
	v_writelane_b32 v255, s6, 13
	s_nop 1
	v_writelane_b32 v255, s7, 14
	v_readlane_b32 s6, v253, 8
	v_readlane_b32 s7, v253, 9
	s_andn2_b64 vcc, exec, s[6:7]
	s_cbranch_vccnz .LBB0_183
	v_lshlrev_b32_e32 v1, 4, v0
	v_and_b32_e32 v2, 64, v232
	v_and_b32_e32 v94, 16, v1
	v_xor_b32_e32 v1, 1, v232
	v_add_u32_e32 v2, 64, v2
	v_cmp_lt_i32_e32 vcc, v1, v2
	v_ashrrev_i32_e32 v95, 1, v0
	s_movk_i32 s3, 0x7f
	v_cndmask_b32_e32 v1, v232, v1, vcc
	v_lshlrev_b32_e32 v99, 2, v1
	v_mul_lo_u32 v1, v95, s89
	v_lshlrev_b32_e32 v3, 1, v94
	v_cmp_lt_i32_e64 s[8:9], s3, v95
	v_add3_u32 v115, 0, v1, v3
	v_and_b32_e32 v117, 0xff, v0
	v_writelane_b32 v254, s8, 63
	v_ashrrev_i32_e32 v1, 3, v0
	v_bfe_u32 v4, v0, 5, 1
	v_writelane_b32 v255, s9, 0
	v_and_b32_e32 v96, 0xffffffe0, v1
	v_cmp_lt_u32_e64 s[8:9], s3, v117
	v_lshlrev_b32_e32 v7, 2, v4
	s_movk_i32 s3, 0x208
	v_or_b32_e32 v1, 31, v1
	v_and_b32_e32 v120, 31, v0
	v_mul_lo_u32 v10, v1, s3
	v_or_b32_e32 v1, 27, v7
	v_cmp_gt_u32_e64 s[10:11], v1, v120
	v_or_b32_e32 v1, 2, v7
	v_cmp_lt_u32_e64 s[16:17], v120, v1
	v_or_b32_e32 v1, 3, v7
	v_cmp_lt_u32_e64 s[18:19], v120, v1
	v_or_b32_e32 v1, 8, v7
	v_cmp_lt_u32_e64 s[20:21], v120, v1
	v_or_b32_e32 v1, 9, v7
	v_cmp_lt_u32_e64 s[22:23], v120, v1
	v_or_b32_e32 v1, 10, v7
	v_cmp_lt_u32_e64 s[24:25], v120, v1
	v_or_b32_e32 v1, 11, v7
	s_load_dwordx2 s[6:7], s[0:1], 0x98
	v_cmp_lt_u32_e64 s[26:27], v120, v1
	v_or_b32_e32 v1, 16, v7
	v_cmp_lt_u32_e64 s[28:29], v120, v1
	v_or_b32_e32 v1, 17, v7
	v_bfe_u32 v119, v0, 6, 2
	v_ashrrev_i32_e32 v0, 2, v0
	v_cmp_lt_u32_e64 s[30:31], v120, v1
	v_or_b32_e32 v1, 18, v7
	v_writelane_b32 v255, s8, 7
	v_and_b32_e32 v121, 0xffffffc0, v0
	v_xor_b32_e32 v0, 32, v232
	v_cmp_lt_u32_e64 s[34:35], v120, v1
	v_or_b32_e32 v1, 19, v7
	v_writelane_b32 v255, s9, 8
	v_cmp_lt_i32_e32 vcc, v0, v2
	v_lshlrev_b32_e32 v2, 2, v94
	v_mov_b32_e32 v3, v193
	v_cmp_lt_u32_e64 s[36:37], v120, v1
	v_or_b32_e32 v1, 24, v7
	v_cndmask_b32_e32 v0, v232, v0, vcc
	s_waitcnt lgkmcnt(0)
	v_lshl_add_u64 v[100:101], s[6:7], 0, v[2:3]
	v_readlane_b32 s6, v255, 9
	v_cmp_lt_u32_e64 s[38:39], v120, v1
	v_or_b32_e32 v1, 25, v7
	v_lshlrev_b32_e32 v192, 3, v4
	v_lshlrev_b32_e32 v122, 2, v0
	v_lshlrev_b32_e32 v0, 4, v4
	v_lshlrev_b32_e32 v4, 5, v4
	v_mov_b32_e32 v5, v193
	v_readlane_b32 s7, v255, 10
	v_cmp_lt_u32_e64 s[40:41], v120, v1
	v_or_b32_e32 v1, 26, v7
	v_add_u32_e32 v98, 0, v0
	v_lshl_add_u64 v[102:103], s[6:7], 0, v[4:5]
	v_cmp_lt_u32_e64 s[42:43], v120, v1
	v_or_b32_e32 v1, v121, v120
	v_readlane_b32 s6, v254, 36
	v_lshl_add_u32 v6, v117, 1, 0
	v_sub_u32_e32 v8, v98, v192
	v_mul_lo_u32 v9, v96, s3
	v_add_u32_e32 v124, 0x80, v1
	v_mov_b32_e32 v1, v193
	v_readlane_b32 s7, v254, 37
	v_lshl_add_u64 v[110:111], s[82:83], 0, v[192:193]
	v_writelane_b32 v255, s82, 17
	v_add_u32_e32 v116, 0xffffff80, v95
	v_ashrrev_i32_e32 v97, 31, v96
	v_add_u32_e32 v118, 0xffffff80, v117
	v_cmp_lt_u32_e64 s[12:13], v120, v7
	v_cmp_le_u32_e64 s[14:15], v120, v7
	v_cmp_lt_u32_e64 s[44:45], v7, v120
	v_mad_u32_u24 v123, v120, s3, v8
	v_lshl_add_u64 v[104:105], s[46:47], 0, v[2:3]
	v_lshl_add_u64 v[106:107], s[6:7], 0, v[0:1]
	v_lshl_add_u64 v[108:109], s[46:47], 0, v[4:5]
	v_add_u32_e32 v125, v6, v10
	v_add_u32_e32 v126, v6, v9
	v_readlane_b32 s3, v253, 0
	v_readlane_b32 s51, v253, 63
	s_nop 0
	s_cmp_lg_u32 s51, 0x100
	s_cbranch_scc1 .Lat_keep
	s_lshr_b32 s50, s3, 5
	s_lshl_b32 s50, s50, 3
	s_bfe_u32 s51, s3, 0x20003
	s_or_b32 s50, s50, s51
	s_and_b32 s3, s3, 7
	s_lshl_b32 s3, s3, 6
	s_or_b32 s3, s3, s50
.Lat_keep:
	v_writelane_b32 v255, s83, 18

.LBB0_181:
	v_or_b32_e32 v62, s86, v121
	v_ashrrev_i32_e32 v63, 5, v62
	v_cmp_lt_i32_e32 vcc, 3, v63
	v_cndmask_b32_e64 v0, 0, 1, s[48:49]
	s_or_b64 s[46:47], s[8:9], vcc
	s_and_b64 s[80:81], s[12:13], s[46:47]
	s_and_b64 s[82:83], s[14:15], s[46:47]
	s_and_b64 s[76:77], s[16:17], s[46:47]
	s_and_b64 s[78:79], s[18:19], s[46:47]
	s_and_b64 s[72:73], s[20:21], s[46:47]
	s_and_b64 s[74:75], s[22:23], s[46:47]
	s_and_b64 s[68:69], s[24:25], s[46:47]
	s_and_b64 s[70:71], s[26:27], s[46:47]
	s_and_b64 s[64:65], s[28:29], s[46:47]
	s_and_b64 s[66:67], s[30:31], s[46:47]
	s_and_b64 s[60:61], s[34:35], s[46:47]
	s_and_b64 s[62:63], s[36:37], s[46:47]
	s_and_b64 s[56:57], s[38:39], s[46:47]
	s_and_b64 s[58:59], s[40:41], s[46:47]
	s_and_b64 s[52:53], s[42:43], s[46:47]
	s_and_b64 s[54:55], s[10:11], s[46:47]
	v_cmp_ne_u32_e64 s[46:47], 1, v0
	v_or_b32_e32 v0, s86, v60
	v_ashrrev_i32_e32 v1, 31, v0
	v_lshl_add_u64 v[2:3], s[6:7], 0, v[0:1]
	v_lshlrev_b64 v[52:53], 11, v[2:3]
	v_lshl_add_u64 v[2:3], v[48:49], 0, v[52:53]
	global_load_dwordx4 v[16:19], v[2:3], off
	global_load_dwordx4 v[64:67], v[2:3], off offset:32
	global_load_dwordx4 v[20:23], v[2:3], off offset:64
	global_load_dwordx4 v[68:71], v[2:3], off offset:96
	v_lshlrev_b64 v[0:1], 8, v[0:1]
	v_lshl_add_u64 v[56:57], v[108:109], 0, v[0:1]
	global_load_dwordx4 v[32:35], v[102:103], off offset:80
	global_load_dwordx4 v[36:39], v[102:103], off offset:64
	global_load_dwordx4 v[24:27], v[102:103], off offset:208
	global_load_dwordx4 v[28:31], v[102:103], off offset:192
	global_load_dwordx4 v[0:3], v[56:57], off offset:80
	global_load_dwordx4 v[8:11], v[56:57], off offset:64
	global_load_dwordx4 v[4:7], v[56:57], off offset:208
	global_load_dwordx4 v[12:15], v[56:57], off offset:192
	s_mov_b32 s86, 0x800000
	v_cmp_lt_i32_e32 vcc, 2, v63
	s_or_b64 s[50:51], s[8:9], vcc
	v_cmp_lt_i32_e32 vcc, 1, v63
	s_or_b64 s[48:49], s[8:9], vcc
	v_cmp_lt_i32_e32 vcc, 0, v63
	s_or_b64 vcc, s[8:9], vcc
	v_lshl_add_u64 v[52:53], v[50:51], 0, v[52:53]
	s_waitcnt vmcnt(11)
	v_lshlrev_b32_e32 v166, 16, v16
	s_waitcnt vmcnt(10)
	v_lshlrev_b32_e32 v42, 16, v67
	v_and_b32_e32 v43, 0xffff0000, v67
	s_waitcnt vmcnt(8)
	v_lshlrev_b32_e32 v40, 16, v71
	v_and_b32_e32 v41, 0xffff0000, v71
	v_lshlrev_b32_e32 v92, 16, v66
	v_and_b32_e32 v93, 0xffff0000, v66
	v_lshlrev_b32_e32 v54, 16, v70
	v_and_b32_e32 v55, 0xffff0000, v70
	v_lshlrev_b32_e32 v134, 16, v65
	v_and_b32_e32 v135, 0xffff0000, v65
	v_lshlrev_b32_e32 v58, 16, v69
	v_and_b32_e32 v59, 0xffff0000, v69
	v_lshlrev_b32_e32 v140, 16, v64
	v_and_b32_e32 v141, 0xffff0000, v64
	v_lshlrev_b32_e32 v142, 16, v68
	v_and_b32_e32 v143, 0xffff0000, v68
	global_load_dwordx4 v[64:67], v[102:103], off offset:16
	global_load_dwordx4 v[68:71], v[102:103], off
	global_load_dwordx4 v[72:75], v[102:103], off offset:144
	global_load_dwordx4 v[76:79], v[102:103], off offset:128
	global_load_dwordx4 v[80:83], v[56:57], off offset:16
	global_load_dwordx4 v[84:87], v[56:57], off
	global_load_dwordx4 v[88:91], v[56:57], off offset:144
	global_load_dwordx4 v[128:131], v[56:57], off offset:128
	v_and_b32_e32 v167, 0xffff0000, v16
	v_lshlrev_b32_e32 v158, 16, v17
	v_and_b32_e32 v159, 0xffff0000, v17
	v_lshlrev_b32_e32 v160, 16, v21
	v_and_b32_e32 v161, 0xffff0000, v21
	v_lshlrev_b32_e32 v16, 16, v20
	v_and_b32_e32 v17, 0xffff0000, v20
	v_pk_mul_f32 v[20:21], v[166:167], v[166:167]
	v_pk_mul_f32 v[162:163], v[158:159], v[158:159]
	v_add_f32_e32 v20, v20, v21
	v_lshlrev_b32_e32 v56, 16, v18
	v_and_b32_e32 v57, 0xffff0000, v18
	v_add_f32_e32 v20, v162, v20
	v_lshlrev_b32_e32 v148, 16, v19
	v_and_b32_e32 v149, 0xffff0000, v19
	v_lshlrev_b32_e32 v150, 16, v23
	v_and_b32_e32 v151, 0xffff0000, v23
	v_lshlrev_b32_e32 v18, 16, v22
	v_and_b32_e32 v19, 0xffff0000, v22
	v_pk_mul_f32 v[22:23], v[56:57], v[56:57]
	v_add_f32_e32 v20, v163, v20
	v_add_f32_e32 v20, v22, v20
	v_pk_mul_f32 v[152:153], v[148:149], v[148:149]
	v_add_f32_e32 v20, v23, v20
	v_add_f32_e32 v20, v152, v20
	v_pk_mul_f32 v[144:145], v[140:141], v[140:141]
	v_add_f32_e32 v20, v153, v20
	v_add_f32_e32 v20, v144, v20
	v_pk_mul_f32 v[136:137], v[134:135], v[134:135]
	v_add_f32_e32 v20, v145, v20
	v_add_f32_e32 v20, v136, v20
	v_pk_mul_f32 v[112:113], v[92:93], v[92:93]
	v_add_f32_e32 v20, v137, v20
	v_add_f32_e32 v20, v112, v20
	v_pk_mul_f32 v[46:47], v[42:43], v[42:43]
	v_add_f32_e32 v20, v113, v20
	v_add_f32_e32 v20, v46, v20
	v_pk_mul_f32 v[168:169], v[16:17], v[16:17]
	v_add_f32_e32 v20, v47, v20
	v_add_f32_e32 v20, v168, v20
	v_pk_mul_f32 v[164:165], v[160:161], v[160:161]
	v_add_f32_e32 v20, v169, v20
	v_add_f32_e32 v20, v164, v20
	v_pk_mul_f32 v[156:157], v[18:19], v[18:19]
	v_add_f32_e32 v20, v165, v20
	v_add_f32_e32 v20, v156, v20
	v_pk_mul_f32 v[154:155], v[150:151], v[150:151]
	v_add_f32_e32 v20, v157, v20
	v_add_f32_e32 v20, v154, v20
	v_pk_mul_f32 v[146:147], v[142:143], v[142:143]
	v_add_f32_e32 v20, v155, v20
	v_add_f32_e32 v20, v146, v20
	v_pk_mul_f32 v[138:139], v[58:59], v[58:59]
	v_add_f32_e32 v20, v147, v20
	v_add_f32_e32 v20, v138, v20
	v_pk_mul_f32 v[132:133], v[54:55], v[54:55]
	v_add_f32_e32 v20, v139, v20
	v_add_f32_e32 v20, v132, v20
	v_pk_mul_f32 v[44:45], v[40:41], v[40:41]
	v_add_f32_e32 v20, v133, v20
	v_add_f32_e32 v20, v44, v20
	v_add_f32_e32 v20, v45, v20
	ds_bpermute_b32 v21, v122, v20
	v_add_u32_e32 v136, 3, v63
	s_waitcnt lgkmcnt(0)
	v_add_f32_e32 v20, v20, v21
	v_fmamk_f32 v20, v20, 0x3c800000, v226
	v_cmp_gt_f32_e64 s[86:87], s86, v20
	v_mul_f32_e32 v21, 0x4b800000, v20
	s_nop 0
	v_cndmask_b32_e64 v20, v20, v21, s[86:87]
	v_rsq_f32_e32 v20, v20
	s_nop 0
	v_mul_f32_e32 v21, 0x45800000, v20
	v_cndmask_b32_e64 v20, v20, v21, s[86:87]
	s_waitcnt vmcnt(15)
	v_pk_mul_f32 v[34:35], v[34:35], v[20:21] op_sel_hi:[1,0]
	s_waitcnt vmcnt(7)
	v_pk_mul_f32 v[46:47], v[64:65], v[20:21] op_sel_hi:[1,0]
	v_pk_mul_f32 v[34:35], v[34:35], v[42:43]
	s_waitcnt vmcnt(4)
	v_pk_mul_f32 v[42:43], v[76:77], v[20:21] op_sel_hi:[1,0]
	v_pk_mul_f32 v[64:65], v[72:73], v[20:21] op_sel_hi:[1,0]
	v_pk_mul_f32 v[22:23], v[68:69], v[20:21] op_sel_hi:[1,0]
	v_pk_mul_f32 v[44:45], v[70:71], v[20:21] op_sel_hi:[1,0]
	v_pk_mul_f32 v[46:47], v[46:47], v[56:57]
	v_pk_mul_f32 v[56:57], v[66:67], v[20:21] op_sel_hi:[1,0]
	v_pk_mul_f32 v[36:37], v[36:37], v[20:21] op_sel_hi:[1,0]
	v_pk_mul_f32 v[38:39], v[38:39], v[20:21] op_sel_hi:[1,0]
	v_pk_mul_f32 v[32:33], v[32:33], v[20:21] op_sel_hi:[1,0]
	v_pk_mul_f32 v[16:17], v[42:43], v[16:17]
	v_pk_mul_f32 v[42:43], v[78:79], v[20:21] op_sel_hi:[1,0]
	v_pk_mul_f32 v[18:19], v[64:65], v[18:19]
	v_pk_mul_f32 v[64:65], v[74:75], v[20:21] op_sel_hi:[1,0]
	v_pk_mul_f32 v[28:29], v[28:29], v[20:21] op_sel_hi:[1,0]
	v_pk_mul_f32 v[30:31], v[30:31], v[20:21] op_sel_hi:[1,0]
	v_pk_mul_f32 v[24:25], v[24:25], v[20:21] op_sel_hi:[1,0]
	v_pk_mul_f32 v[20:21], v[26:27], v[20:21] op_sel_hi:[1,0]
	v_pk_mul_f32 v[22:23], v[22:23], v[166:167]
	v_pk_mul_f32 v[26:27], v[20:21], v[40:41]
	s_waitcnt vmcnt(0)
	v_pk_mul_f32 v[20:21], v[128:129], v[16:17]
	v_pk_mul_f32 v[16:17], v[84:85], v[16:17]
	v_pk_mul_f32 v[42:43], v[42:43], v[160:161]
	v_pk_fma_f32 v[16:17], v[128:129], v[22:23], v[16:17]
	v_pk_mul_f32 v[44:45], v[44:45], v[158:159]
	v_pk_fma_f32 v[20:21], v[84:85], v[22:23], v[20:21] neg_lo:[0,0,1] neg_hi:[0,0,1]
	v_pk_mul_f32 v[22:23], v[16:17], s[4:5] op_sel_hi:[1,0]
	v_pk_mul_f32 v[16:17], v[130:131], v[42:43]
	v_pk_mul_f32 v[64:65], v[64:65], v[150:151]
	v_pk_fma_f32 v[16:17], v[86:87], v[44:45], v[16:17] neg_lo:[0,0,1] neg_hi:[0,0,1]
	v_pk_mul_f32 v[56:57], v[56:57], v[148:149]
	v_pk_mul_f32 v[40:41], v[16:17], s[4:5] op_sel_hi:[1,0]
	v_pk_mul_f32 v[16:17], v[86:87], v[42:43]
	v_pk_mul_f32 v[24:25], v[24:25], v[54:55]
	v_pk_fma_f32 v[16:17], v[130:131], v[44:45], v[16:17]
	v_pk_mul_f32 v[36:37], v[36:37], v[140:141]
	v_pk_mul_f32 v[42:43], v[16:17], s[4:5] op_sel_hi:[1,0]
	v_pk_mul_f32 v[16:17], v[18:19], v[88:89]
	v_pk_mul_f32 v[28:29], v[28:29], v[142:143]
	v_pk_fma_f32 v[16:17], v[46:47], v[80:81], v[16:17] neg_lo:[0,0,1] neg_hi:[0,0,1]
	v_pk_mul_f32 v[38:39], v[38:39], v[134:135]
	v_pk_mul_f32 v[44:45], v[16:17], s[4:5] op_sel_hi:[1,0]
	v_pk_mul_f32 v[16:17], v[88:89], v[46:47]
	v_pk_mul_f32 v[30:31], v[30:31], v[58:59]
	v_pk_fma_f32 v[16:17], v[80:81], v[18:19], v[16:17]
	v_pk_mul_f32 v[32:33], v[32:33], v[92:93]
	v_pk_mul_f32 v[46:47], v[16:17], s[4:5] op_sel_hi:[1,0]
	v_pk_mul_f32 v[16:17], v[64:65], v[90:91]
	v_pk_mul_f32 v[20:21], v[20:21], s[4:5] op_sel_hi:[1,0]
	v_pk_fma_f32 v[16:17], v[56:57], v[82:83], v[16:17] neg_lo:[0,0,1] neg_hi:[0,0,1]
	v_cvt_pk_bf16_f32 v18, v44, v45
	v_pk_mul_f32 v[54:55], v[16:17], s[4:5] op_sel_hi:[1,0]
	v_pk_mul_f32 v[16:17], v[56:57], v[90:91]
	v_cvt_pk_bf16_f32 v19, v54, v55
	v_pk_fma_f32 v[16:17], v[64:65], v[82:83], v[16:17]
	v_add_u32_e32 v84, 1, v63
	v_pk_mul_f32 v[56:57], v[16:17], s[4:5] op_sel_hi:[1,0]
	v_cvt_pk_bf16_f32 v17, v40, v41
	v_pk_mul_f32 v[40:41], v[28:29], v[12:13]
	v_pk_mul_f32 v[12:13], v[36:37], v[12:13]
	v_pk_fma_f32 v[40:41], v[36:37], v[8:9], v[40:41] neg_lo:[0,0,1] neg_hi:[0,0,1]
	v_pk_fma_f32 v[8:9], v[28:29], v[8:9], v[12:13]
	v_pk_mul_f32 v[12:13], v[30:31], v[14:15]
	v_pk_mul_f32 v[14:15], v[38:39], v[14:15]
	v_pk_fma_f32 v[12:13], v[38:39], v[10:11], v[12:13] neg_lo:[0,0,1] neg_hi:[0,0,1]
	v_pk_fma_f32 v[10:11], v[30:31], v[10:11], v[14:15]
	v_pk_mul_f32 v[14:15], v[24:25], v[4:5]
	v_pk_mul_f32 v[4:5], v[32:33], v[4:5]
	v_pk_fma_f32 v[14:15], v[32:33], v[0:1], v[14:15] neg_lo:[0,0,1] neg_hi:[0,0,1]
	v_pk_fma_f32 v[0:1], v[24:25], v[0:1], v[4:5]
	v_pk_mul_f32 v[4:5], v[26:27], v[6:7]
	v_pk_mul_f32 v[0:1], v[0:1], s[4:5] op_sel_hi:[1,0]
	v_pk_fma_f32 v[4:5], v[34:35], v[2:3], v[4:5] neg_lo:[0,0,1] neg_hi:[0,0,1]
	v_pk_mul_f32 v[6:7], v[34:35], v[6:7]
	v_pk_mul_f32 v[4:5], v[4:5], s[4:5] op_sel_hi:[1,0]
	v_pk_fma_f32 v[2:3], v[26:27], v[2:3], v[6:7]
	v_cvt_pk_bf16_f32 v30, v0, v1
	v_or_b32_e32 v0, v62, v120
	v_pk_mul_f32 v[40:41], v[40:41], s[4:5] op_sel_hi:[1,0]
	v_pk_mul_f32 v[2:3], v[2:3], s[4:5] op_sel_hi:[1,0]
	v_cvt_pk_bf16_f32 v27, v4, v5
	v_mad_u64_u32 v[4:5], s[86:87], v0, s89, v[98:99]
	v_cvt_pk_bf16_f32 v16, v20, v21
	v_cvt_pk_bf16_f32 v21, v42, v43
	v_cvt_pk_bf16_f32 v24, v40, v41
	v_cvt_pk_bf16_f32 v31, v2, v3
	ds_read_b128 v[0:3], v4
	ds_read_b128 v[32:35], v4 offset:32
	ds_read_b128 v[36:39], v4 offset:64
	ds_read_b128 v[40:43], v4 offset:96
	v_pk_mul_f32 v[8:9], v[8:9], s[4:5] op_sel_hi:[1,0]
	v_pk_mul_f32 v[12:13], v[12:13], s[4:5] op_sel_hi:[1,0]
	v_pk_mul_f32 v[10:11], v[10:11], s[4:5] op_sel_hi:[1,0]
	v_pk_mul_f32 v[14:15], v[14:15], s[4:5] op_sel_hi:[1,0]
	v_cvt_pk_bf16_f32 v28, v8, v9
	v_cvt_pk_bf16_f32 v25, v12, v13
	v_cvt_pk_bf16_f32 v29, v10, v11
	v_cvt_pk_bf16_f32 v26, v14, v15
	s_waitcnt lgkmcnt(3)
	v_mfma_f32_32x32x16_bf16 v[0:15], v[0:3], v[16:19], 0
	v_cvt_pk_bf16_f32 v20, v22, v23
	v_cvt_pk_bf16_f32 v22, v46, v47
	v_cvt_pk_bf16_f32 v23, v56, v57
	v_add_u32_e32 v92, 2, v63
	v_add_u32_e32 v63, 4, v63
	s_mov_b32 s87, 0x800000
	s_mov_b32 s86, 32
	s_waitcnt lgkmcnt(2)
	v_mfma_f32_32x32x16_bf16 v[0:15], v[32:35], v[24:27], v[0:15]
	s_waitcnt lgkmcnt(1)
	v_mfma_f32_32x32x16_bf16 v[0:15], v[36:39], v[20:23], v[0:15]
	s_waitcnt lgkmcnt(0)
	v_mfma_f32_32x32x16_bf16 v[0:15], v[40:43], v[28:31], v[0:15]
	s_nop 11
	v_cndmask_b32_e64 v44, v233, v0, s[80:81]
	v_cndmask_b32_e64 v45, v233, v1, s[82:83]
	v_max3_f32 v0, v61, v44, v45
	v_cndmask_b32_e64 v46, v233, v2, s[76:77]
	v_cndmask_b32_e64 v47, v233, v3, s[78:79]
	v_max3_f32 v0, v0, v46, v47
	v_cndmask_b32_e64 v54, v233, v4, s[72:73]
	v_cndmask_b32_e64 v55, v233, v5, s[74:75]
	v_max3_f32 v0, v0, v54, v55
	v_cndmask_b32_e64 v56, v233, v6, s[68:69]
	v_cndmask_b32_e64 v57, v233, v7, s[70:71]
	v_max3_f32 v0, v0, v56, v57
	v_cndmask_b32_e64 v58, v233, v8, s[64:65]
	v_cndmask_b32_e64 v59, v233, v9, s[66:67]
	v_max3_f32 v0, v0, v58, v59
	v_cndmask_b32_e64 v64, v233, v10, s[60:61]
	v_cndmask_b32_e64 v65, v233, v11, s[62:63]
	v_max3_f32 v0, v0, v64, v65
	v_cndmask_b32_e64 v66, v233, v12, s[56:57]
	v_cndmask_b32_e64 v67, v233, v13, s[58:59]
	v_max3_f32 v0, v0, v66, v67
	v_cndmask_b32_e64 v68, v233, v14, s[52:53]
	v_cndmask_b32_e64 v69, v233, v15, s[54:55]
	v_max3_f32 v70, v0, v68, v69
	v_lshl_or_b32 v0, v84, 5, v120
	v_mad_u64_u32 v[4:5], s[52:53], v0, s89, v[98:99]
	ds_read_b128 v[0:3], v4
	ds_read_b128 v[32:35], v4 offset:32
	ds_read_b128 v[36:39], v4 offset:64
	ds_read_b128 v[40:43], v4 offset:96
	s_waitcnt lgkmcnt(3)
	v_mfma_f32_32x32x16_bf16 v[0:15], v[0:3], v[16:19], 0
	s_waitcnt lgkmcnt(2)
	v_mfma_f32_32x32x16_bf16 v[0:15], v[32:35], v[24:27], v[0:15]
	s_waitcnt lgkmcnt(1)
	v_mfma_f32_32x32x16_bf16 v[0:15], v[36:39], v[20:23], v[0:15]
	s_waitcnt lgkmcnt(0)
	v_mfma_f32_32x32x16_bf16 v[0:15], v[40:43], v[28:31], v[0:15]
	s_nop 11
	v_cndmask_b32_e64 v86, v233, v1, s[50:51]
	v_cndmask_b32_e64 v87, v233, v0, s[50:51]
	v_cndmask_b32_e64 v83, v233, v3, s[50:51]
	v_cndmask_b32_e64 v85, v233, v2, s[50:51]
	v_max3_f32 v0, v70, v87, v86
	v_cndmask_b32_e64 v81, v233, v5, s[50:51]
	v_cndmask_b32_e64 v82, v233, v4, s[50:51]
	v_max3_f32 v0, v0, v85, v83
	v_cndmask_b32_e64 v79, v233, v7, s[50:51]
	v_cndmask_b32_e64 v80, v233, v6, s[50:51]
	v_max3_f32 v0, v0, v82, v81
	v_cndmask_b32_e64 v77, v233, v9, s[50:51]
	v_cndmask_b32_e64 v78, v233, v8, s[50:51]
	v_max3_f32 v0, v0, v80, v79
	v_cndmask_b32_e64 v75, v233, v11, s[50:51]
	v_cndmask_b32_e64 v76, v233, v10, s[50:51]
	v_max3_f32 v0, v0, v78, v77
	v_cndmask_b32_e64 v73, v233, v13, s[50:51]
	v_cndmask_b32_e64 v74, v233, v12, s[50:51]
	v_max3_f32 v0, v0, v76, v75
	v_cndmask_b32_e64 v71, v233, v15, s[50:51]
	v_cndmask_b32_e64 v72, v233, v14, s[50:51]
	v_max3_f32 v0, v0, v74, v73
	v_max3_f32 v70, v0, v72, v71
	v_lshl_or_b32 v0, v92, 5, v120
	v_mad_u64_u32 v[4:5], s[50:51], v0, s89, v[98:99]
	ds_read_b128 v[0:3], v4
	ds_read_b128 v[32:35], v4 offset:32
	ds_read_b128 v[36:39], v4 offset:64
	ds_read_b128 v[40:43], v4 offset:96
	s_waitcnt lgkmcnt(3)
	v_mfma_f32_32x32x16_bf16 v[0:15], v[0:3], v[16:19], 0
	v_lshl_add_u32 v92, v92, 6, v123
	s_waitcnt lgkmcnt(2)
	v_mfma_f32_32x32x16_bf16 v[0:15], v[32:35], v[24:27], v[0:15]
	s_waitcnt lgkmcnt(1)
	v_mfma_f32_32x32x16_bf16 v[0:15], v[36:39], v[20:23], v[0:15]
	s_waitcnt lgkmcnt(0)
	v_mfma_f32_32x32x16_bf16 v[0:15], v[40:43], v[28:31], v[0:15]
	s_nop 11
	v_cndmask_b32_e64 v133, v233, v1, s[48:49]
	v_cndmask_b32_e64 v134, v233, v0, s[48:49]
	v_cndmask_b32_e64 v131, v233, v3, s[48:49]
	v_cndmask_b32_e64 v132, v233, v2, s[48:49]
	v_max3_f32 v0, v70, v134, v133
	v_cndmask_b32_e64 v129, v233, v5, s[48:49]
	v_cndmask_b32_e64 v130, v233, v4, s[48:49]
	v_max3_f32 v0, v0, v132, v131
	v_cndmask_b32_e64 v127, v233, v7, s[48:49]
	v_cndmask_b32_e64 v128, v233, v6, s[48:49]
	v_max3_f32 v0, v0, v130, v129
	v_cndmask_b32_e64 v113, v233, v9, s[48:49]
	v_cndmask_b32_e64 v114, v233, v8, s[48:49]
	v_max3_f32 v0, v0, v128, v127
	v_cndmask_b32_e64 v93, v233, v11, s[48:49]
	v_cndmask_b32_e64 v112, v233, v10, s[48:49]
	v_max3_f32 v0, v0, v114, v113
	v_cndmask_b32_e64 v90, v233, v13, s[48:49]
	v_cndmask_b32_e64 v91, v233, v12, s[48:49]
	v_max3_f32 v0, v0, v112, v93
	v_cndmask_b32_e64 v88, v233, v15, s[48:49]
	v_cndmask_b32_e64 v89, v233, v14, s[48:49]
	v_max3_f32 v0, v0, v91, v90
	v_max3_f32 v70, v0, v89, v88
	v_lshl_or_b32 v0, v136, 5, v120
	v_mad_u64_u32 v[4:5], s[48:49], v0, s89, v[98:99]
	ds_read_b128 v[0:3], v4
	ds_read_b128 v[32:35], v4 offset:32
	ds_read_b128 v[36:39], v4 offset:64
	ds_read_b128 v[40:43], v4 offset:96
	s_waitcnt lgkmcnt(3)
	v_mfma_f32_32x32x16_bf16 v[0:15], v[0:3], v[16:19], 0
	s_waitcnt lgkmcnt(2)
	v_mfma_f32_32x32x16_bf16 v[0:15], v[32:35], v[24:27], v[0:15]
	s_waitcnt lgkmcnt(1)
	v_mfma_f32_32x32x16_bf16 v[0:15], v[36:39], v[20:23], v[0:15]
	s_waitcnt lgkmcnt(0)
	v_mfma_f32_32x32x16_bf16 v[0:15], v[40:43], v[28:31], v[0:15]
	s_nop 11
	v_cndmask_b32_e32 v150, v233, v1, vcc
	v_cndmask_b32_e32 v151, v233, v0, vcc
	v_cndmask_b32_e32 v148, v233, v3, vcc
	v_cndmask_b32_e32 v149, v233, v2, vcc
	v_max3_f32 v0, v70, v151, v150
	v_cndmask_b32_e32 v146, v233, v5, vcc
	v_cndmask_b32_e32 v147, v233, v4, vcc
	v_max3_f32 v0, v0, v149, v148
	v_cndmask_b32_e32 v144, v233, v7, vcc
	v_cndmask_b32_e32 v145, v233, v6, vcc
	v_max3_f32 v0, v0, v147, v146
	v_cndmask_b32_e32 v142, v233, v9, vcc
	v_cndmask_b32_e32 v143, v233, v8, vcc
	v_max3_f32 v0, v0, v145, v144
	v_cndmask_b32_e32 v140, v233, v11, vcc
	v_cndmask_b32_e32 v141, v233, v10, vcc
	v_max3_f32 v0, v0, v143, v142
	v_cndmask_b32_e32 v138, v233, v13, vcc
	v_cndmask_b32_e32 v139, v233, v12, vcc
	v_max3_f32 v0, v0, v141, v140
	v_cndmask_b32_e32 v135, v233, v15, vcc
	v_cndmask_b32_e32 v137, v233, v14, vcc
	v_max3_f32 v0, v0, v139, v138
	v_max3_f32 v70, v0, v137, v135
	v_lshl_or_b32 v0, v63, 5, v120
	v_mad_u64_u32 v[4:5], s[48:49], v0, s89, v[98:99]
	ds_read_b128 v[0:3], v4
	ds_read_b128 v[32:35], v4 offset:32
	ds_read_b128 v[36:39], v4 offset:64
	ds_read_b128 v[40:43], v4 offset:96
	s_waitcnt lgkmcnt(3)
	v_mfma_f32_32x32x16_bf16 v[0:15], v[0:3], v[16:19], 0
	v_lshl_add_u32 v63, v63, 6, v123
	s_waitcnt lgkmcnt(2)
	v_mfma_f32_32x32x16_bf16 v[0:15], v[32:35], v[24:27], v[0:15]
	s_waitcnt lgkmcnt(1)
	v_mfma_f32_32x32x16_bf16 v[0:15], v[36:39], v[20:23], v[0:15]
	s_waitcnt lgkmcnt(0)
	v_mfma_f32_32x32x16_bf16 v[0:15], v[40:43], v[28:31], v[0:15]
	s_nop 11
	v_cndmask_b32_e64 v0, v0, v233, s[12:13]
	v_cndmask_b32_e64 v1, v233, v1, s[44:45]
	v_max3_f32 v16, v70, v0, v1
	v_cndmask_b32_e64 v2, v2, v233, s[16:17]
	v_cndmask_b32_e64 v3, v3, v233, s[18:19]
	v_max3_f32 v16, v16, v2, v3
	v_cndmask_b32_e64 v4, v4, v233, s[20:21]
	v_cndmask_b32_e64 v5, v5, v233, s[22:23]
	v_max3_f32 v16, v16, v4, v5
	v_cndmask_b32_e64 v6, v6, v233, s[24:25]
	v_cndmask_b32_e64 v7, v7, v233, s[26:27]
	v_max3_f32 v16, v16, v6, v7
	v_cndmask_b32_e64 v8, v8, v233, s[28:29]
	v_cndmask_b32_e64 v9, v9, v233, s[30:31]
	v_max3_f32 v16, v16, v8, v9
	v_cndmask_b32_e64 v10, v10, v233, s[34:35]
	v_cndmask_b32_e64 v11, v11, v233, s[36:37]
	v_max3_f32 v16, v16, v10, v11
	v_cndmask_b32_e64 v12, v12, v233, s[38:39]
	v_cndmask_b32_e64 v13, v13, v233, s[40:41]
	v_max3_f32 v16, v16, v12, v13
	v_cndmask_b32_e64 v14, v14, v233, s[42:43]
	v_cndmask_b32_e64 v15, v15, v233, s[10:11]
	v_max3_f32 v16, v16, v14, v15
	ds_bpermute_b32 v17, v122, v16
	s_waitcnt lgkmcnt(0)
	v_max_f32_e32 v17, v17, v17
	v_max_f32_e32 v16, v16, v17
	v_sub_f32_e32 v17, v44, v16
	v_sub_f32_e32 v18, v45, v16
	v_exp_f32_e32 v17, v17
	v_exp_f32_e32 v18, v18
	v_sub_f32_e32 v19, v46, v16
	v_exp_f32_e32 v19, v19
	v_sub_f32_e32 v20, v47, v16
	v_exp_f32_e32 v20, v20
	v_sub_f32_e32 v21, v54, v16
	v_sub_f32_e32 v32, v69, v16
	v_exp_f32_e32 v21, v21
	v_sub_f32_e32 v22, v55, v16
	v_exp_f32_e32 v40, v32
	v_cvt_pk_bf16_f32 v32, v17, v18
	v_add_f32_e32 v17, 0, v17
	v_exp_f32_e32 v22, v22
	v_sub_f32_e32 v23, v56, v16
	v_add_f32_e32 v17, v18, v17
	v_exp_f32_e32 v23, v23
	v_sub_f32_e32 v24, v57, v16
	v_add_f32_e32 v17, v19, v17
	v_exp_f32_e32 v24, v24
	v_sub_f32_e32 v25, v58, v16
	v_add_f32_e32 v17, v20, v17
	v_exp_f32_e32 v25, v25
	v_sub_f32_e32 v26, v59, v16
	v_add_f32_e32 v17, v21, v17
	v_exp_f32_e32 v26, v26
	v_sub_f32_e32 v27, v64, v16
	v_add_f32_e32 v17, v22, v17
	v_exp_f32_e32 v27, v27
	v_sub_f32_e32 v28, v65, v16
	v_add_f32_e32 v17, v23, v17
	v_exp_f32_e32 v28, v28
	v_sub_f32_e32 v29, v66, v16
	v_add_f32_e32 v17, v24, v17
	v_exp_f32_e32 v29, v29
	v_sub_f32_e32 v30, v67, v16
	v_add_f32_e32 v17, v25, v17
	v_exp_f32_e32 v30, v30
	v_sub_f32_e32 v31, v68, v16
	v_add_f32_e32 v17, v26, v17
	v_exp_f32_e32 v31, v31
	v_add_f32_e32 v17, v27, v17
	v_add_f32_e32 v17, v28, v17
	v_sub_f32_e32 v18, v87, v16
	v_cvt_pk_bf16_f32 v33, v19, v20
	v_add_f32_e32 v17, v29, v17
	v_exp_f32_e32 v18, v18
	v_sub_f32_e32 v19, v86, v16
	v_add_f32_e32 v17, v30, v17
	v_exp_f32_e32 v19, v19
	v_sub_f32_e32 v20, v85, v16
	v_cvt_pk_bf16_f32 v34, v21, v22
	v_add_f32_e32 v17, v31, v17
	v_exp_f32_e32 v20, v20
	v_sub_f32_e32 v21, v83, v16
	v_add_f32_e32 v17, v40, v17
	v_exp_f32_e32 v21, v21
	v_sub_f32_e32 v22, v82, v16
	v_cvt_pk_bf16_f32 v35, v23, v24
	v_exp_f32_e32 v22, v22
	v_sub_f32_e32 v23, v81, v16
	v_add_f32_e32 v17, v18, v17
	v_exp_f32_e32 v23, v23
	v_sub_f32_e32 v24, v80, v16
	v_add_f32_e32 v17, v19, v17
	v_cvt_pk_bf16_f32 v36, v25, v26
	v_exp_f32_e32 v24, v24
	v_sub_f32_e32 v25, v79, v16
	v_add_f32_e32 v17, v20, v17
	v_exp_f32_e32 v25, v25
	v_sub_f32_e32 v26, v78, v16
	v_add_f32_e32 v17, v21, v17
	v_cvt_pk_bf16_f32 v37, v27, v28
	v_exp_f32_e32 v26, v26
	v_sub_f32_e32 v27, v77, v16
	v_add_f32_e32 v17, v22, v17
	v_exp_f32_e32 v27, v27
	v_sub_f32_e32 v28, v76, v16
	v_add_f32_e32 v17, v23, v17
	v_cvt_pk_bf16_f32 v38, v29, v30
	v_exp_f32_e32 v28, v28
	v_sub_f32_e32 v29, v75, v16
	v_add_f32_e32 v17, v24, v17
	v_exp_f32_e32 v29, v29
	v_sub_f32_e32 v30, v74, v16
	v_add_f32_e32 v17, v25, v17
	v_cvt_pk_bf16_f32 v39, v31, v40
	v_exp_f32_e32 v30, v30
	v_sub_f32_e32 v31, v73, v16
	v_add_f32_e32 v17, v26, v17
	v_exp_f32_e32 v31, v31
	v_sub_f32_e32 v40, v72, v16
	v_add_f32_e32 v17, v27, v17
	v_exp_f32_e32 v54, v40
	v_sub_f32_e32 v40, v71, v16
	v_add_f32_e32 v17, v28, v17
	v_exp_f32_e32 v55, v40
	v_cvt_pk_bf16_f32 v40, v18, v19
	v_add_f32_e32 v17, v29, v17
	v_sub_f32_e32 v18, v134, v16
	v_add_f32_e32 v17, v30, v17
	v_exp_f32_e32 v18, v18
	v_sub_f32_e32 v19, v133, v16
	v_cvt_pk_bf16_f32 v41, v20, v21
	v_add_f32_e32 v17, v31, v17
	v_exp_f32_e32 v19, v19
	v_sub_f32_e32 v20, v132, v16
	v_add_f32_e32 v17, v54, v17
	v_exp_f32_e32 v20, v20
	v_sub_f32_e32 v21, v131, v16
	v_cvt_pk_bf16_f32 v42, v22, v23
	v_add_f32_e32 v17, v55, v17
	v_exp_f32_e32 v21, v21
	v_sub_f32_e32 v22, v130, v16
	v_exp_f32_e32 v22, v22
	v_sub_f32_e32 v23, v129, v16
	v_add_f32_e32 v17, v18, v17
	v_cvt_pk_bf16_f32 v43, v24, v25
	v_exp_f32_e32 v23, v23
	v_sub_f32_e32 v24, v128, v16
	v_add_f32_e32 v17, v19, v17
	v_exp_f32_e32 v24, v24
	v_sub_f32_e32 v25, v127, v16
	v_add_f32_e32 v17, v20, v17
	v_cvt_pk_bf16_f32 v44, v26, v27
	v_exp_f32_e32 v25, v25
	v_sub_f32_e32 v26, v114, v16
	v_add_f32_e32 v17, v21, v17
	v_exp_f32_e32 v26, v26
	v_sub_f32_e32 v27, v113, v16
	v_add_f32_e32 v17, v22, v17
	v_cvt_pk_bf16_f32 v45, v28, v29
	v_exp_f32_e32 v27, v27
	v_sub_f32_e32 v28, v112, v16
	v_add_f32_e32 v17, v23, v17
	v_exp_f32_e32 v28, v28
	v_sub_f32_e32 v29, v93, v16
	v_add_f32_e32 v17, v24, v17
	v_cvt_pk_bf16_f32 v46, v30, v31
	v_exp_f32_e32 v29, v29
	v_sub_f32_e32 v30, v91, v16
	v_add_f32_e32 v17, v25, v17
	v_exp_f32_e32 v30, v30
	v_sub_f32_e32 v31, v90, v16
	v_add_f32_e32 v17, v26, v17
	v_cvt_pk_bf16_f32 v47, v54, v55
	v_exp_f32_e32 v31, v31
	v_sub_f32_e32 v54, v89, v16
	v_add_f32_e32 v17, v27, v17
	v_exp_f32_e32 v58, v54
	v_sub_f32_e32 v54, v88, v16
	v_add_f32_e32 v17, v28, v17
	v_exp_f32_e32 v59, v54
	v_cvt_pk_bf16_f32 v54, v18, v19
	v_add_f32_e32 v17, v29, v17
	v_sub_f32_e32 v18, v151, v16
	v_add_f32_e32 v17, v30, v17
	v_exp_f32_e32 v18, v18
	v_sub_f32_e32 v19, v150, v16
	v_cvt_pk_bf16_f32 v55, v20, v21
	v_add_f32_e32 v17, v31, v17
	v_exp_f32_e32 v19, v19
	v_sub_f32_e32 v20, v149, v16
	v_add_f32_e32 v17, v58, v17
	v_exp_f32_e32 v20, v20
	v_sub_f32_e32 v21, v148, v16
	v_cvt_pk_bf16_f32 v56, v22, v23
	v_add_f32_e32 v17, v59, v17
	v_exp_f32_e32 v21, v21
	v_sub_f32_e32 v22, v147, v16
	v_exp_f32_e32 v22, v22
	v_sub_f32_e32 v23, v146, v16
	v_add_f32_e32 v17, v18, v17
	v_cvt_pk_bf16_f32 v57, v24, v25
	v_exp_f32_e32 v23, v23
	v_sub_f32_e32 v24, v145, v16
	v_add_f32_e32 v17, v19, v17
	v_exp_f32_e32 v24, v24
	v_sub_f32_e32 v25, v144, v16
	v_add_f32_e32 v17, v20, v17
	v_cvt_pk_bf16_f32 v64, v26, v27
	v_exp_f32_e32 v25, v25
	v_sub_f32_e32 v26, v143, v16
	v_add_f32_e32 v17, v21, v17
	v_exp_f32_e32 v26, v26
	v_sub_f32_e32 v27, v142, v16
	v_add_f32_e32 v17, v22, v17
	v_cvt_pk_bf16_f32 v65, v28, v29
	v_exp_f32_e32 v27, v27
	v_sub_f32_e32 v28, v141, v16
	v_add_f32_e32 v17, v23, v17
	v_exp_f32_e32 v28, v28
	v_sub_f32_e32 v29, v140, v16
	v_add_f32_e32 v17, v24, v17
	v_cvt_pk_bf16_f32 v66, v30, v31
	v_exp_f32_e32 v29, v29
	v_sub_f32_e32 v30, v139, v16
	v_add_f32_e32 v17, v25, v17
	v_exp_f32_e32 v30, v30
	v_sub_f32_e32 v31, v138, v16
	v_add_f32_e32 v17, v26, v17
	v_cvt_pk_bf16_f32 v67, v58, v59
	v_exp_f32_e32 v31, v31
	v_sub_f32_e32 v58, v137, v16
	v_add_f32_e32 v17, v27, v17
	v_exp_f32_e32 v58, v58
	v_sub_f32_e32 v59, v135, v16
	v_add_f32_e32 v17, v28, v17
	v_exp_f32_e32 v59, v59
	v_add_f32_e32 v17, v29, v17
	v_sub_f32_e32 v0, v0, v16
	v_sub_f32_e32 v1, v1, v16
	v_add_f32_e32 v17, v30, v17
	v_exp_f32_e32 v0, v0
	v_exp_f32_e32 v1, v1
	v_add_f32_e32 v17, v31, v17
	v_sub_f32_e32 v2, v2, v16
	v_add_f32_e32 v17, v58, v17
	v_exp_f32_e32 v2, v2
	v_sub_f32_e32 v3, v3, v16
	v_add_f32_e32 v17, v59, v17
	v_exp_f32_e32 v3, v3
	v_sub_f32_e32 v4, v4, v16
	v_exp_f32_e32 v4, v4
	v_sub_f32_e32 v5, v5, v16
	v_cvt_pk_bf16_f32 v76, v0, v1
	v_add_f32_e32 v0, v0, v17
	v_exp_f32_e32 v5, v5
	v_sub_f32_e32 v6, v6, v16
	v_add_f32_e32 v0, v1, v0
	v_exp_f32_e32 v6, v6
	v_sub_f32_e32 v7, v7, v16
	v_add_f32_e32 v0, v2, v0
	v_exp_f32_e32 v7, v7
	v_sub_f32_e32 v8, v8, v16
	v_add_f32_e32 v0, v3, v0
	v_exp_f32_e32 v8, v8
	v_sub_f32_e32 v9, v9, v16
	v_add_f32_e32 v0, v4, v0
	v_exp_f32_e32 v9, v9
	v_sub_f32_e32 v10, v10, v16
	v_add_f32_e32 v0, v5, v0
	v_exp_f32_e32 v10, v10
	v_sub_f32_e32 v11, v11, v16
	v_add_f32_e32 v0, v6, v0
	v_exp_f32_e32 v11, v11
	v_sub_f32_e32 v12, v12, v16
	v_add_f32_e32 v0, v7, v0
	v_exp_f32_e32 v12, v12
	v_sub_f32_e32 v13, v13, v16
	v_add_f32_e32 v0, v8, v0
	v_exp_f32_e32 v13, v13
	v_sub_f32_e32 v14, v14, v16
	v_add_f32_e32 v0, v9, v0
	v_exp_f32_e32 v14, v14
	v_sub_f32_e32 v15, v15, v16
	v_add_f32_e32 v0, v10, v0
	v_exp_f32_e32 v15, v15
	v_add_f32_e32 v0, v11, v0
	v_add_f32_e32 v0, v12, v0
	v_add_f32_e32 v0, v13, v0
	v_add_f32_e32 v0, v14, v0
	v_add_f32_e32 v0, v15, v0
	ds_bpermute_b32 v1, v122, v0
	v_cvt_pk_bf16_f32 v77, v2, v3
	v_cvt_pk_bf16_f32 v78, v4, v5
	v_cvt_pk_bf16_f32 v75, v58, v59
	v_lshl_add_u32 v59, v62, 1, v123
	s_waitcnt lgkmcnt(0)
	v_add_f32_e32 v0, v0, v1
	v_sub_f32_e32 v1, v61, v16
	v_exp_f32_e32 v1, v1
	v_cvt_pk_bf16_f32 v68, v18, v19
	v_lshl_add_u32 v62, v84, 6, v123
	v_lshl_add_u32 v93, v136, 6, v123
	v_add_f32_e32 v0, v1, v0
	v_div_scale_f32 v1, s[48:49], v0, v0, 1.0
	v_rcp_f32_e32 v2, v1
	v_cvt_pk_bf16_f32 v69, v20, v21
	v_cvt_pk_bf16_f32 v70, v22, v23
	v_cvt_pk_bf16_f32 v71, v24, v25
	v_fma_f32 v3, -v1, v2, 1.0
	v_fmac_f32_e32 v2, v3, v2
	v_div_scale_f32 v3, vcc, 1.0, v0, 1.0
	v_mul_f32_e32 v4, v3, v2
	v_fma_f32 v5, -v1, v4, v3
	v_fmac_f32_e32 v4, v5, v2
	v_fma_f32 v1, -v1, v4, v3
	v_div_fmas_f32 v1, v1, v2, v4
	v_add_u32_e32 v4, 0x9000, v59
	v_div_fixup_f32 v58, v1, v0, 1.0
	ds_read2_b64 v[0:3], v4 offset1:2
	ds_read2_b64 v[16:19], v4 offset0:4 offset1:6
	v_add_u32_e32 v4, 0x9000, v62
	ds_read2_b64 v[84:87], v4 offset1:2
	ds_read2_b64 v[88:91], v4 offset0:4 offset1:6
	v_add_u32_e32 v4, 0x9000, v92
	ds_read2_b64 v[128:131], v4 offset1:2
	ds_read2_b64 v[132:135], v4 offset0:4 offset1:6
	v_add_u32_e32 v4, 0x9000, v93
	ds_read2_b64 v[136:139], v4 offset1:2
	ds_read2_b64 v[140:143], v4 offset0:4 offset1:6
	v_add_u32_e32 v4, 0x9000, v63
	v_cvt_pk_bf16_f32 v72, v26, v27
	v_cvt_pk_bf16_f32 v73, v28, v29
	v_cvt_pk_bf16_f32 v74, v30, v31
	v_cvt_pk_bf16_f32 v79, v6, v7
	v_cvt_pk_bf16_f32 v80, v8, v9
	v_cvt_pk_bf16_f32 v81, v10, v11
	v_cvt_pk_bf16_f32 v82, v12, v13
	v_cvt_pk_bf16_f32 v83, v14, v15
	ds_read2_b64 v[144:147], v4 offset1:2
	ds_read2_b64 v[148:151], v4 offset0:4 offset1:6
	s_waitcnt lgkmcnt(9)
	v_mfma_f32_32x32x16_bf16 v[0:15], v[0:3], v[32:35], 0
	s_mov_b64 s[48:49], 0
	s_and_b64 vcc, exec, s[46:47]
	s_waitcnt lgkmcnt(8)
	v_mfma_f32_32x32x16_bf16 v[16:31], v[16:19], v[36:39], 0
	s_waitcnt lgkmcnt(7)
	v_mfma_f32_32x32x16_bf16 v[0:15], v[84:87], v[40:43], v[0:15]
	s_waitcnt lgkmcnt(6)
	v_mfma_f32_32x32x16_bf16 v[16:31], v[88:91], v[44:47], v[16:31]
	s_waitcnt lgkmcnt(5)
	v_mfma_f32_32x32x16_bf16 v[0:15], v[128:131], v[54:57], v[0:15]
	s_waitcnt lgkmcnt(4)
	v_mfma_f32_32x32x16_bf16 v[16:31], v[132:135], v[64:67], v[16:31]
	s_waitcnt lgkmcnt(3)
	v_mfma_f32_32x32x16_bf16 v[0:15], v[136:139], v[68:71], v[0:15]
	s_waitcnt lgkmcnt(2)
	v_mfma_f32_32x32x16_bf16 v[16:31], v[140:143], v[72:75], v[16:31]
	s_waitcnt lgkmcnt(1)
	v_mfma_f32_32x32x16_bf16 v[0:15], v[144:147], v[76:79], v[0:15]
	s_waitcnt lgkmcnt(0)
	v_mfma_f32_32x32x16_bf16 v[16:31], v[148:151], v[80:83], v[16:31]
	s_nop 11
	v_pk_add_f32 v[2:3], v[2:3], v[18:19]
	v_pk_add_f32 v[0:1], v[0:1], v[16:17]
	v_pk_mul_f32 v[2:3], v[2:3], v[58:59] op_sel_hi:[1,0]
	v_pk_mul_f32 v[0:1], v[0:1], v[58:59] op_sel_hi:[1,0]
	v_pk_add_f32 v[6:7], v[6:7], v[22:23]
	v_pk_add_f32 v[4:5], v[4:5], v[20:21]
	v_cvt_pk_bf16_f32 v0, v0, v1
	v_cvt_pk_bf16_f32 v1, v2, v3
	global_store_dwordx2 v[52:53], v[0:1], off
	v_pk_mul_f32 v[0:1], v[4:5], v[58:59] op_sel_hi:[1,0]
	v_pk_mul_f32 v[2:3], v[6:7], v[58:59] op_sel_hi:[1,0]
	v_pk_add_f32 v[10:11], v[10:11], v[26:27]
	v_pk_add_f32 v[8:9], v[8:9], v[24:25]
	v_cvt_pk_bf16_f32 v0, v0, v1
	v_cvt_pk_bf16_f32 v1, v2, v3
	global_store_dwordx2 v[52:53], v[0:1], off offset:16
	v_pk_mul_f32 v[0:1], v[8:9], v[58:59] op_sel_hi:[1,0]
	v_pk_mul_f32 v[2:3], v[10:11], v[58:59] op_sel_hi:[1,0]
	v_pk_add_f32 v[14:15], v[14:15], v[30:31]
	v_pk_add_f32 v[12:13], v[12:13], v[28:29]
	v_cvt_pk_bf16_f32 v0, v0, v1
	v_cvt_pk_bf16_f32 v1, v2, v3
	global_store_dwordx2 v[52:53], v[0:1], off offset:32
	v_pk_mul_f32 v[0:1], v[12:13], v[58:59] op_sel_hi:[1,0]
	v_pk_mul_f32 v[2:3], v[14:15], v[58:59] op_sel_hi:[1,0]
	v_cvt_pk_bf16_f32 v0, v0, v1
	v_cvt_pk_bf16_f32 v1, v2, v3
	global_store_dwordx2 v[52:53], v[0:1], off offset:48
	v_add_u32_e32 v4, 0xd000, v59
	ds_read2_b64 v[0:3], v4 offset0:32 offset1:34
	ds_read2_b64 v[16:19], v4 offset0:36 offset1:38
	v_add_u32_e32 v4, 0xd000, v62
	ds_read2_b64 v[84:87], v4 offset0:32 offset1:34
	ds_read2_b64 v[88:91], v4 offset0:36 offset1:38
	v_add_u32_e32 v4, 0xd000, v92
	ds_read2_b64 v[128:131], v4 offset0:32 offset1:34
	ds_read2_b64 v[132:135], v4 offset0:36 offset1:38
	v_add_u32_e32 v4, 0xd000, v93
	ds_read2_b64 v[136:139], v4 offset0:32 offset1:34
	ds_read2_b64 v[140:143], v4 offset0:36 offset1:38
	v_add_u32_e32 v4, 0xd000, v63
	ds_read2_b64 v[144:147], v4 offset0:32 offset1:34
	ds_read2_b64 v[148:151], v4 offset0:36 offset1:38
	s_waitcnt lgkmcnt(9)
	v_mfma_f32_32x32x16_bf16 v[0:15], v[0:3], v[32:35], 0
	s_waitcnt lgkmcnt(8)
	v_mfma_f32_32x32x16_bf16 v[16:31], v[16:19], v[36:39], 0
	s_waitcnt lgkmcnt(7)
	v_mfma_f32_32x32x16_bf16 v[0:15], v[84:87], v[40:43], v[0:15]
	s_waitcnt lgkmcnt(6)
	v_mfma_f32_32x32x16_bf16 v[16:31], v[88:91], v[44:47], v[16:31]
	s_waitcnt lgkmcnt(5)
	v_mfma_f32_32x32x16_bf16 v[0:15], v[128:131], v[54:57], v[0:15]
	s_waitcnt lgkmcnt(4)
	v_mfma_f32_32x32x16_bf16 v[16:31], v[132:135], v[64:67], v[16:31]
	s_waitcnt lgkmcnt(3)
	v_mfma_f32_32x32x16_bf16 v[0:15], v[136:139], v[68:71], v[0:15]
	s_waitcnt lgkmcnt(2)
	v_mfma_f32_32x32x16_bf16 v[16:31], v[140:143], v[72:75], v[16:31]
	s_waitcnt lgkmcnt(1)
	v_mfma_f32_32x32x16_bf16 v[0:15], v[144:147], v[76:79], v[0:15]
	s_waitcnt lgkmcnt(0)
	v_mfma_f32_32x32x16_bf16 v[16:31], v[148:151], v[80:83], v[16:31]
	s_nop 11
	v_pk_add_f32 v[2:3], v[2:3], v[18:19]
	v_pk_add_f32 v[0:1], v[0:1], v[16:17]
	v_pk_mul_f32 v[2:3], v[2:3], v[58:59] op_sel_hi:[1,0]
	v_pk_mul_f32 v[0:1], v[0:1], v[58:59] op_sel_hi:[1,0]
	v_pk_add_f32 v[6:7], v[6:7], v[22:23]
	v_pk_add_f32 v[4:5], v[4:5], v[20:21]
	v_cvt_pk_bf16_f32 v0, v0, v1
	v_cvt_pk_bf16_f32 v1, v2, v3
	global_store_dwordx2 v[52:53], v[0:1], off offset:64
	v_pk_mul_f32 v[0:1], v[4:5], v[58:59] op_sel_hi:[1,0]
	v_pk_mul_f32 v[2:3], v[6:7], v[58:59] op_sel_hi:[1,0]
	v_pk_add_f32 v[10:11], v[10:11], v[26:27]
	v_pk_add_f32 v[8:9], v[8:9], v[24:25]
	v_cvt_pk_bf16_f32 v0, v0, v1
	v_cvt_pk_bf16_f32 v1, v2, v3
	global_store_dwordx2 v[52:53], v[0:1], off offset:80
	v_pk_mul_f32 v[0:1], v[8:9], v[58:59] op_sel_hi:[1,0]
	v_pk_mul_f32 v[2:3], v[10:11], v[58:59] op_sel_hi:[1,0]
	v_pk_add_f32 v[14:15], v[14:15], v[30:31]
	v_pk_add_f32 v[12:13], v[12:13], v[28:29]
	v_cvt_pk_bf16_f32 v0, v0, v1
	v_cvt_pk_bf16_f32 v1, v2, v3
	global_store_dwordx2 v[52:53], v[0:1], off offset:96
	v_pk_mul_f32 v[0:1], v[12:13], v[58:59] op_sel_hi:[1,0]
	v_pk_mul_f32 v[2:3], v[14:15], v[58:59] op_sel_hi:[1,0]
	v_cvt_pk_bf16_f32 v0, v0, v1
	v_cvt_pk_bf16_f32 v1, v2, v3
	global_store_dwordx2 v[52:53], v[0:1], off offset:112
	s_cbranch_vccz .LBB0_181
	s_barrier
	s_load_dwordx2 s[56:57], s[0:1], 0xd8
	v_readlane_b32 s72, v253, 63
	v_readlane_b32 s66, v254, 1
	v_readlane_b32 s73, v254, 0
	s_cmp_lg_u32 s72, 0x100
	s_cselect_b32 s50, s72, 4
	s_add_i32 s3, s3, s50
	v_readlane_b32 s67, v254, 2
	v_readlane_b32 s60, v254, 47
	v_readlane_b32 s76, v254, 50
	v_readlane_b32 s82, v255, 17
	s_cmpk_gt_i32 s3, 0x1ff
	s_cselect_b32 s50, 1, 0
	s_bitcmp0_b32 s3, 2
	s_cselect_b32 s51, 1, 0
	s_cmp_eq_u32 s72, 0x100
	s_cselect_b32 s50, s51, s50
	s_cmp_lg_u32 s50, 0
	v_readlane_b32 s68, v254, 3
	v_readlane_b32 s69, v254, 4
	s_movk_i32 s70, 0x1000
	s_mov_b32 s71, 0x20000
	s_mov_b32 s73, 0x1ffff
	s_mov_b32 s74, 0x50000
	s_mov_b32 s75, 0xe000
	s_movk_i32 s78, 0x3000
	s_movk_i32 s79, 0x5000
	s_movk_i32 s80, 0x7000
	s_mov_b32 s81, 0x8000
	s_mov_b32 s59, 0xa000
	s_mov_b32 s67, 0xc000
	s_mov_b32 s64, 0xf000
	v_readlane_b32 s61, v254, 48
	v_readlane_b32 s62, v254, 49
	v_readlane_b32 s77, v254, 51
	v_readlane_b32 s83, v255, 18
	s_cbranch_scc0 .LBB0_158

.LBB0_215:
	v_add_u32_e32 v100, 0, v60
	v_add_u32_e32 v94, 0x10c00, v100
	v_add_u32_e32 v101, 0, v93
	ds_read_b128 v[94:97], v94
	ds_read2st64_b32 v[98:99], v101 offset1:1
	s_add_i32 s22, s22, -8
	v_add_u32_e32 v93, 0x800, v93
	v_add_u32_e32 v60, 32, v60
	s_cmp_eq_u32 s22, 0
	s_waitcnt lgkmcnt(0)
	v_fmac_f32_e32 v61, v94, v98
	v_fmac_f32_e32 v61, v95, v99
	ds_read2st64_b32 v[94:95], v101 offset0:2 offset1:3
	s_waitcnt lgkmcnt(0)
	v_fmac_f32_e32 v61, v96, v94
	v_add_u32_e32 v94, 0x10c10, v100
	v_fmac_f32_e32 v61, v97, v95
	ds_read_b128 v[94:97], v94
	ds_read2st64_b32 v[98:99], v101 offset0:4 offset1:5
	s_waitcnt lgkmcnt(0)
	v_fmac_f32_e32 v61, v94, v98
	v_fmac_f32_e32 v61, v95, v99
	ds_read2st64_b32 v[94:95], v101 offset0:6 offset1:7
	s_waitcnt lgkmcnt(0)
	v_fmac_f32_e32 v61, v96, v94
	v_fmac_f32_e32 v61, v97, v95
	s_cbranch_scc0 .LBB0_215
	ds_write_b32 v73, v61
	s_waitcnt lgkmcnt(0)
	s_barrier
	s_and_saveexec_b64 s[22:23], s[12:13]
	s_cbranch_execz .LBB0_185
	v_sub_f32_e32 v57, v57, v59
	v_mul_f32_e32 v57, 0x3fb8aa3b, v57
	ds_read_b32 v95, v73 offset:256
	v_exp_f32_e32 v60, v57
	v_add_f32_e32 v94, v62, v63
	s_lshl_b64 s[24:25], s[24:25], 11
	v_lshlrev_b32_e32 v58, 6, v58
	s_waitcnt lgkmcnt(0)
	v_pk_add_f32 v[60:61], v[60:61], v[94:95]
	s_add_u32 s24, s82, s24
	v_div_scale_f32 v57, s[26:27], v60, v60, 1.0
	v_rcp_f32_e32 v59, v57
	v_div_scale_f32 v62, vcc, 1.0, v60, 1.0
	s_movk_i32 s26, 0x7fff
	v_fma_f32 v63, -v57, v59, 1.0
	v_fmac_f32_e32 v59, v63, v59
	v_mul_f32_e32 v63, v62, v59
	v_fma_f32 v93, -v57, v63, v62
	v_fmac_f32_e32 v63, v93, v59
	v_fma_f32 v57, -v57, v63, v62
	v_div_fmas_f32 v57, v57, v59, v63
	v_div_fixup_f32 v57, v57, v60, 1.0
	v_mul_f32_e32 v57, v57, v61
	v_bfe_u32 v59, v57, 16, 1
	v_add3_u32 v60, v57, v59, s26
	v_ashrrev_i32_e32 v59, 31, v58
	s_addc_u32 s25, s83, s25
	v_lshl_add_u64 v[58:59], v[58:59], 1, s[24:25]
	v_mov_b32_e32 v57, v193
	v_lshl_add_u64 v[58:59], v[58:59], 0, v[56:57]
	global_store_short_d16_hi v[58:59], v60, off sc1
	s_branch .LBB0_185

.LBB0_1202:
	s_andn2_saveexec_b64 s[8:9], s[8:9]
	s_cbranch_execz .LBB0_1222
	s_mov_b64 s[8:9], exec
	s_cmp_lt_i32 s54, 1
	s_cbranch_scc1 .Lxb_wb
	s_movk_i32 s101, 0xd4
	s_cmp_lt_i32 s54, 16
	s_cselect_b32 s101, 0xda, s101
	s_and_b32 s100, s54, 7
	s_lshr_b32 s100, s101, s100
	s_bitcmp1_b32 s100, 0
	s_cbranch_scc0 .Lxb_wb
	v_mov_b32_e32 v20, 0x20008
	ds_read_b32 v20, v20
	s_waitcnt lgkmcnt(0)
	v_readfirstlane_b32 s100, v20
	s_nop 0
	s_cmp_eq_u32 s100, 1
	s_cbranch_scc1 .Lxb_nowb
